# attention: the next QK block's first four K fragment reads issued before the 16-exp block that precedes it (LDS latency under the exps)
# baseline (speedup 1.0000x reference)
.LBB0_1035:
	v_exp_f32_e32 v218, v88
	v_exp_f32_e32 v225, v89
	s_add_i32 s0, s75, 1
	s_cmp_lg_u32 s75, 2
	s_cselect_b32 s76, s0, 0
	v_lshl_add_u32 v223, s76, 13, v190
	v_add_u32_e32 v68, v223, v191
	ds_read_b128 v[64:67], v68 offset:49152
	ds_read_b128 v[68:71], v68 offset:53248
	v_add_u32_e32 v116, v223, v192
	ds_read_b128 v[112:115], v116 offset:49152
	ds_read_b128 v[116:119], v116 offset:53248
	v_exp_f32_e32 v120, v80
	v_exp_f32_e32 v121, v81
	v_exp_f32_e32 v122, v82
	v_exp_f32_e32 v123, v83
	v_exp_f32_e32 v124, v84
	v_exp_f32_e32 v125, v85
	v_exp_f32_e32 v126, v86
	v_exp_f32_e32 v127, v87
	v_exp_f32_e32 v226, v90
	v_exp_f32_e32 v227, v91
	v_exp_f32_e32 v228, v92
	v_exp_f32_e32 v229, v93
	v_exp_f32_e32 v230, v94
	v_exp_f32_e32 v231, v95
	s_setprio 1
	s_waitcnt lgkmcnt(0)
	v_mfma_f32_32x32x16_bf16 v[80:95], v[64:67], v[108:111], 0
	v_mfma_f32_32x32x16_bf16 v[64:79], v[68:71], v[108:111], 0
	v_mfma_f32_32x32x16_bf16 v[80:95], v[112:115], v[104:107], v[80:95]
	v_mfma_f32_32x32x16_bf16 v[64:79], v[116:119], v[104:107], v[64:79]
	v_add_u32_e32 v116, v223, v193
	ds_read_b128 v[112:115], v116 offset:49152
	ds_read_b128 v[116:119], v116 offset:53248
	s_waitcnt lgkmcnt(0)
	v_mfma_f32_32x32x16_bf16 v[80:95], v[112:115], v[100:103], v[80:95]
	v_mfma_f32_32x32x16_bf16 v[64:79], v[116:119], v[100:103], v[64:79]
	v_add_u32_e32 v116, v223, v194
	ds_read_b128 v[112:115], v116 offset:49152
	ds_read_b128 v[116:119], v116 offset:53248
	s_waitcnt lgkmcnt(0)
	v_mfma_f32_32x32x16_bf16 v[80:95], v[112:115], v[96:99], v[80:95]
	v_mfma_f32_32x32x16_bf16 v[64:79], v[116:119], v[96:99], v[64:79]
	s_setprio 0
	v_exp_f32_e32 v160, v160
	v_exp_f32_e32 v161, v161
	v_add_f32_e32 v112, v120, v160
	v_add_f32_e32 v113, v121, v161
	v_exp_f32_e32 v162, v162
	v_add_f32_e32 v112, v112, v122
	v_add_f32_e32 v113, v113, v123
	v_exp_f32_e32 v163, v163
	v_add_f32_e32 v112, v112, v162
	v_add_f32_e32 v113, v113, v163
	v_exp_f32_e32 v164, v164
	v_add_f32_e32 v112, v112, v124
	v_add_f32_e32 v113, v113, v125
	v_exp_f32_e32 v165, v165
	v_add_f32_e32 v112, v112, v164
	v_add_f32_e32 v113, v113, v165
	v_exp_f32_e32 v166, v166
	v_add_f32_e32 v112, v112, v126
	v_add_f32_e32 v113, v113, v127
	v_exp_f32_e32 v167, v167
	v_add_f32_e32 v112, v112, v166
	v_add_f32_e32 v113, v113, v167
	v_exp_f32_e32 v168, v168
	v_add_f32_e32 v112, v112, v218
	v_add_f32_e32 v113, v113, v225
	v_exp_f32_e32 v169, v169
	v_add_f32_e32 v112, v112, v168
	v_add_f32_e32 v113, v113, v169
	v_exp_f32_e32 v170, v170
	v_add_f32_e32 v112, v112, v226
	v_add_f32_e32 v113, v113, v227
	v_exp_f32_e32 v171, v171
	v_add_f32_e32 v112, v112, v170
	v_add_f32_e32 v113, v113, v171
	v_exp_f32_e32 v172, v172
	v_add_f32_e32 v112, v112, v228
	v_add_f32_e32 v113, v113, v229
	v_exp_f32_e32 v173, v173
	v_exp_f32_e32 v174, v174
	v_exp_f32_e32 v175, v175
	v_add_f32_e32 v112, v112, v172
	v_add_f32_e32 v113, v113, v173
	s_nop 0
	v_add_f32_e32 v112, v112, v230
	v_add_f32_e32 v113, v113, v231
	s_nop 0
	v_add_f32_e32 v112, v112, v174
	v_add_f32_e32 v113, v113, v175
	s_nop 0
	v_add_f32_e32 v223, v112, v113
	v_cvt_pk_bf16_f32 v112, v120, v121
	v_cvt_pk_bf16_f32 v113, v122, v123
	v_cvt_pk_bf16_f32 v114, v124, v125
	v_cvt_pk_bf16_f32 v115, v126, v127
	v_cvt_pk_bf16_f32 v116, v218, v225
	s_nop 0
	v_mov_b32_e32 v224, v223
	s_nop 1
	v_permlane32_swap_b32_e32 v223, v224
	v_cvt_pk_bf16_f32 v117, v226, v227
	v_cvt_pk_bf16_f32 v118, v228, v229
	v_cvt_pk_bf16_f32 v119, v230, v231
	v_cvt_pk_bf16_f32 v120, v160, v161
	v_cvt_pk_bf16_f32 v121, v162, v163
	v_cvt_pk_bf16_f32 v122, v164, v165
	v_cvt_pk_bf16_f32 v123, v166, v167
	v_cvt_pk_bf16_f32 v124, v168, v169
	v_cvt_pk_bf16_f32 v125, v170, v171
	v_cvt_pk_bf16_f32 v126, v172, v173
	v_cvt_pk_bf16_f32 v127, v174, v175
	v_permlane32_swap_b32_e32 v112, v114
	v_permlane32_swap_b32_e32 v113, v115
	v_permlane32_swap_b32_e32 v116, v118
	v_permlane32_swap_b32_e32 v117, v119
	v_permlane32_swap_b32_e32 v120, v122
	v_permlane32_swap_b32_e32 v121, v123
	v_permlane32_swap_b32_e32 v124, v126
	v_permlane32_swap_b32_e32 v125, v127
	s_lshl_b32 s75, s75, 14
	v_add_u32_e32 v226, s75, v187
	ds_read_b64_tr_b16 v[160:161], v226 offset:0
	ds_read_b64_tr_b16 v[162:163], v226 offset:0x800
	ds_read_b64_tr_b16 v[164:165], v226 offset:0x1000
	ds_read_b64_tr_b16 v[166:167], v226 offset:0x1800
	ds_read_b64_tr_b16 v[168:169], v226 offset:0x2000
	ds_read_b64_tr_b16 v[170:171], v226 offset:0x2800
	ds_read_b64_tr_b16 v[172:173], v226 offset:0x3000
	ds_read_b64_tr_b16 v[174:175], v226 offset:0x3800
	s_setprio 1
	s_waitcnt lgkmcnt(6)
	v_mfma_f32_32x32x16_bf16 v[48:63], v[112:115], v[160:163], v[48:63]
	s_waitcnt lgkmcnt(4)
	v_mfma_f32_32x32x16_bf16 v[48:63], v[116:119], v[164:167], v[48:63]
	s_waitcnt lgkmcnt(2)
	v_mfma_f32_32x32x16_bf16 v[48:63], v[120:123], v[168:171], v[48:63]
	s_waitcnt lgkmcnt(0)
	v_mfma_f32_32x32x16_bf16 v[48:63], v[124:127], v[172:175], v[48:63]
	s_setprio 0
	v_max3_f32 v160, v80, v81, v82
	v_max3_f32 v161, v64, v65, v66
	v_max_f32_e32 v162, v79, v79
	v_max3_f32 v160, v160, v83, v84
	v_max3_f32 v161, v161, v67, v68
	v_max_f32_e32 v163, v95, v95
	v_max3_f32 v160, v160, v85, v86
	v_max3_f32 v161, v161, v69, v70
	v_max_f32_e32 v162, v163, v162
	v_max3_f32 v160, v160, v87, v88
	v_max3_f32 v161, v161, v71, v72
	s_nop 0
	v_max3_f32 v160, v160, v89, v90
	v_max3_f32 v161, v161, v73, v74
	s_nop 0
	v_max3_f32 v160, v160, v91, v92
	v_max3_f32 v161, v161, v75, v76
	s_nop 0
	v_max3_f32 v160, v160, v93, v94
	v_max3_f32 v161, v161, v77, v78
	s_nop 0
	v_max3_f32 v160, v160, v161, v162
	s_nop 0
	v_mov_b32_e32 v161, v160
	s_nop 1
	v_permlane32_swap_b32_e32 v160, v161
	v_max_f32_e32 v161, v161, v161
	v_max_f32_e32 v160, v160, v160
	v_max_f32_e32 v218, v160, v161
	ds_read_b64_tr_b16 v[160:161], v226 offset:0x200
	ds_read_b64_tr_b16 v[162:163], v226 offset:0xa00
	ds_read_b64_tr_b16 v[164:165], v226 offset:0x1200
	ds_read_b64_tr_b16 v[166:167], v226 offset:0x1a00
	ds_read_b64_tr_b16 v[168:169], v226 offset:0x2200
	ds_read_b64_tr_b16 v[170:171], v226 offset:0x2a00
	ds_read_b64_tr_b16 v[172:173], v226 offset:0x3200
	ds_read_b64_tr_b16 v[174:175], v226 offset:0x3a00
	s_setprio 1
	s_waitcnt lgkmcnt(6)
	v_mfma_f32_32x32x16_bf16 v[32:47], v[112:115], v[160:163], v[32:47]
	s_waitcnt lgkmcnt(4)
	v_mfma_f32_32x32x16_bf16 v[32:47], v[116:119], v[164:167], v[32:47]
	s_waitcnt lgkmcnt(2)
	v_mfma_f32_32x32x16_bf16 v[32:47], v[120:123], v[168:171], v[32:47]
	s_waitcnt lgkmcnt(0)
	v_mfma_f32_32x32x16_bf16 v[32:47], v[124:127], v[172:175], v[32:47]
	s_setprio 0
	v_sub_f32_e32 v160, v218, v222
	v_cmp_ge_f32_e32 vcc, s71, v160
	s_cmp_eq_u64 vcc, exec
	v_max_f32_e32 v160, v222, v222
	v_max_f32_e32 v225, v160, v218
	s_cselect_b64 s[0:1], -1, 0
	v_cndmask_b32_e64 v218, v225, v222, s[0:1]
	v_mul_f32_e32 v161, 0xbe38aa3b, v218
	v_fma_f32 v80, v80, v197, v161
	v_fma_f32 v81, v81, v197, v161
	v_fma_f32 v82, v82, v197, v161
	v_fma_f32 v83, v83, v197, v161
	v_fma_f32 v84, v84, v197, v161
	v_fma_f32 v85, v85, v197, v161
	v_fma_f32 v86, v86, v197, v161
	v_fma_f32 v87, v87, v197, v161
	v_fma_f32 v88, v88, v197, v161
	v_fma_f32 v89, v89, v197, v161
	v_fma_f32 v90, v90, v197, v161
	v_fma_f32 v91, v91, v197, v161
	v_fma_f32 v92, v92, v197, v161
	v_fma_f32 v93, v93, v197, v161
	v_fma_f32 v94, v94, v197, v161
	v_fma_f32 v95, v95, v197, v161
	v_fma_f32 v174, v64, v197, v161
	v_fma_f32 v175, v65, v197, v161
	v_fma_f32 v172, v66, v197, v161
	v_fma_f32 v173, v67, v197, v161
	v_fma_f32 v170, v68, v197, v161
	v_fma_f32 v171, v69, v197, v161
	v_fma_f32 v168, v70, v197, v161
	v_fma_f32 v169, v71, v197, v161
	v_fma_f32 v166, v72, v197, v161
	v_fma_f32 v167, v73, v197, v161
	v_fma_f32 v164, v74, v197, v161
	v_fma_f32 v165, v75, v197, v161
	v_fma_f32 v162, v76, v197, v161
	v_fma_f32 v163, v77, v197, v161
	v_fma_f32 v160, v78, v197, v161
	v_fma_f32 v161, v79, v197, v161
	ds_read_b64_tr_b16 v[64:65], v226 offset:0x400
	ds_read_b64_tr_b16 v[66:67], v226 offset:0xc00
	ds_read_b64_tr_b16 v[68:69], v226 offset:0x1400
	ds_read_b64_tr_b16 v[70:71], v226 offset:0x1c00
	ds_read_b64_tr_b16 v[72:73], v226 offset:0x2400
	ds_read_b64_tr_b16 v[74:75], v226 offset:0x2c00
	ds_read_b64_tr_b16 v[76:77], v226 offset:0x3400
	ds_read_b64_tr_b16 v[78:79], v226 offset:0x3c00
	s_setprio 1
	s_waitcnt lgkmcnt(6)
	v_mfma_f32_32x32x16_bf16 v[16:31], v[112:115], v[64:67], v[16:31]
	s_waitcnt lgkmcnt(4)
	v_mfma_f32_32x32x16_bf16 v[16:31], v[116:119], v[68:71], v[16:31]
	s_waitcnt lgkmcnt(2)
	v_mfma_f32_32x32x16_bf16 v[16:31], v[120:123], v[72:75], v[16:31]
	s_waitcnt lgkmcnt(0)
	v_mfma_f32_32x32x16_bf16 v[16:31], v[124:127], v[76:79], v[16:31]
	s_setprio 0
	ds_read_b64_tr_b16 v[64:65], v226 offset:0x600
	ds_read_b64_tr_b16 v[66:67], v226 offset:0xe00
	ds_read_b64_tr_b16 v[68:69], v226 offset:0x1600
	ds_read_b64_tr_b16 v[70:71], v226 offset:0x1e00
	ds_read_b64_tr_b16 v[72:73], v226 offset:0x2600
	ds_read_b64_tr_b16 v[74:75], v226 offset:0x2e00
	ds_read_b64_tr_b16 v[76:77], v226 offset:0x3600
	ds_read_b64_tr_b16 v[78:79], v226 offset:0x3e00
	s_setprio 1
	s_waitcnt lgkmcnt(6)
	v_mfma_f32_32x32x16_bf16 v[0:15], v[112:115], v[64:67], v[0:15]
	s_waitcnt lgkmcnt(4)
	v_mfma_f32_32x32x16_bf16 v[0:15], v[116:119], v[68:71], v[0:15]
	s_waitcnt lgkmcnt(2)
	v_mfma_f32_32x32x16_bf16 v[0:15], v[120:123], v[72:75], v[0:15]
	s_waitcnt lgkmcnt(0)
	v_mfma_f32_32x32x16_bf16 v[0:15], v[124:127], v[76:79], v[0:15]
	s_setprio 0
	s_waitcnt vmcnt(0)
	s_barrier
	s_cmp_gt_u32 s74, 28
	s_cselect_b64 s[48:49], -1, 0
	s_and_b64 vcc, exec, s[48:49]
	s_cbranch_vccnz .LBB0_1037
	s_add_i32 s77, s77, s33
	v_lshl_add_u64 v[64:65], v[176:177], 0, s[14:15]
	s_add_i32 m0, s77, 0xc000
	s_add_i32 s75, s51, s75
	global_load_lds_dwordx4 v[64:65], off
	v_lshl_add_u64 v[64:65], v[178:179], 0, s[34:35]
	s_mov_b32 m0, s75
	s_nop 0
	global_load_lds_dwordx4 v[64:65], off
	v_lshl_add_u64 v[64:65], v[180:181], 0, s[34:35]
	s_add_i32 m0, s75, 0x2000
	s_nop 0
	global_load_lds_dwordx4 v[64:65], off

.LBB0_1054:
	v_exp_f32_e32 v227, v88
	v_exp_f32_e32 v232, v89
	s_add_i32 s0, s76, 1
	s_cmp_lg_u32 s76, 2
	s_cselect_b32 s36, s0, 0
	v_lshl_add_u32 v230, s36, 13, v190
	v_add_u32_e32 v68, v230, v191
	ds_read_b128 v[64:67], v68 offset:49152
	ds_read_b128 v[68:71], v68 offset:53248
	v_add_u32_e32 v116, v230, v192
	ds_read_b128 v[112:115], v116 offset:49152
	ds_read_b128 v[116:119], v116 offset:53248
	v_exp_f32_e32 v120, v80
	v_exp_f32_e32 v121, v81
	v_exp_f32_e32 v122, v82
	v_exp_f32_e32 v123, v83
	v_exp_f32_e32 v124, v84
	v_exp_f32_e32 v125, v85
	v_exp_f32_e32 v126, v86
	v_exp_f32_e32 v127, v87
	v_exp_f32_e32 v233, v90
	v_exp_f32_e32 v234, v91
	v_exp_f32_e32 v235, v92
	v_exp_f32_e32 v236, v93
	v_exp_f32_e32 v237, v94
	v_exp_f32_e32 v238, v95
	s_setprio 1
	s_waitcnt lgkmcnt(0)
	v_mfma_f32_32x32x16_bf16 v[80:95], v[64:67], v[108:111], 0
	v_mfma_f32_32x32x16_bf16 v[64:79], v[68:71], v[108:111], 0
	v_mfma_f32_32x32x16_bf16 v[80:95], v[112:115], v[104:107], v[80:95]
	v_mfma_f32_32x32x16_bf16 v[64:79], v[116:119], v[104:107], v[64:79]
	v_add_u32_e32 v116, v230, v193
	ds_read_b128 v[112:115], v116 offset:49152
	ds_read_b128 v[116:119], v116 offset:53248
	s_waitcnt lgkmcnt(0)
	v_mfma_f32_32x32x16_bf16 v[80:95], v[112:115], v[100:103], v[80:95]
	v_mfma_f32_32x32x16_bf16 v[64:79], v[116:119], v[100:103], v[64:79]
	v_add_u32_e32 v116, v230, v194
	ds_read_b128 v[112:115], v116 offset:49152
	ds_read_b128 v[116:119], v116 offset:53248
	s_waitcnt lgkmcnt(0)
	v_mfma_f32_32x32x16_bf16 v[80:95], v[112:115], v[96:99], v[80:95]
	v_mfma_f32_32x32x16_bf16 v[64:79], v[116:119], v[96:99], v[64:79]
	s_setprio 0
	v_exp_f32_e32 v166, v166
	v_exp_f32_e32 v167, v167
	v_add_f32_e32 v112, v120, v166
	v_add_f32_e32 v113, v121, v167
	v_exp_f32_e32 v168, v168
	v_add_f32_e32 v112, v112, v122
	v_add_f32_e32 v113, v113, v123
	v_exp_f32_e32 v169, v169
	v_add_f32_e32 v112, v112, v168
	v_add_f32_e32 v113, v113, v169
	v_exp_f32_e32 v170, v170
	v_add_f32_e32 v112, v112, v124
	v_add_f32_e32 v113, v113, v125
	v_exp_f32_e32 v171, v171
	v_add_f32_e32 v112, v112, v170
	v_add_f32_e32 v113, v113, v171
	v_exp_f32_e32 v172, v172
	v_add_f32_e32 v112, v112, v126
	v_add_f32_e32 v113, v113, v127
	v_exp_f32_e32 v173, v173
	v_add_f32_e32 v112, v112, v172
	v_add_f32_e32 v113, v113, v173
	v_exp_f32_e32 v174, v174
	v_add_f32_e32 v112, v112, v227
	v_add_f32_e32 v113, v113, v232
	v_exp_f32_e32 v175, v175
	v_add_f32_e32 v112, v112, v174
	v_add_f32_e32 v113, v113, v175
	v_exp_f32_e32 v176, v176
	v_add_f32_e32 v112, v112, v233
	v_add_f32_e32 v113, v113, v234
	v_exp_f32_e32 v177, v177
	v_add_f32_e32 v112, v112, v176
	v_add_f32_e32 v113, v113, v177
	v_exp_f32_e32 v178, v178
	v_add_f32_e32 v112, v112, v235
	v_add_f32_e32 v113, v113, v236
	v_exp_f32_e32 v179, v179
	v_exp_f32_e32 v180, v180
	v_exp_f32_e32 v181, v181
	v_add_f32_e32 v112, v112, v178
	v_add_f32_e32 v113, v113, v179
	s_nop 0
	v_add_f32_e32 v112, v112, v237
	v_add_f32_e32 v113, v113, v238
	s_nop 0
	v_add_f32_e32 v112, v112, v180
	v_add_f32_e32 v113, v113, v181
	s_nop 0
	v_add_f32_e32 v230, v112, v113
	v_cvt_pk_bf16_f32 v112, v120, v121
	v_cvt_pk_bf16_f32 v113, v122, v123
	v_cvt_pk_bf16_f32 v114, v124, v125
	v_cvt_pk_bf16_f32 v115, v126, v127
	v_cvt_pk_bf16_f32 v116, v227, v232
	s_nop 0
	v_mov_b32_e32 v231, v230
	s_nop 1
	v_permlane32_swap_b32_e32 v230, v231
	v_cvt_pk_bf16_f32 v117, v233, v234
	v_cvt_pk_bf16_f32 v118, v235, v236
	v_cvt_pk_bf16_f32 v119, v237, v238
	v_cvt_pk_bf16_f32 v120, v166, v167
	v_cvt_pk_bf16_f32 v121, v168, v169
	v_cvt_pk_bf16_f32 v122, v170, v171
	v_cvt_pk_bf16_f32 v123, v172, v173
	v_cvt_pk_bf16_f32 v124, v174, v175
	v_cvt_pk_bf16_f32 v125, v176, v177
	v_cvt_pk_bf16_f32 v126, v178, v179
	v_cvt_pk_bf16_f32 v127, v180, v181
	v_permlane32_swap_b32_e32 v112, v114
	v_permlane32_swap_b32_e32 v113, v115
	v_permlane32_swap_b32_e32 v116, v118
	v_permlane32_swap_b32_e32 v117, v119
	v_permlane32_swap_b32_e32 v120, v122
	v_permlane32_swap_b32_e32 v121, v123
	v_permlane32_swap_b32_e32 v124, v126
	v_permlane32_swap_b32_e32 v125, v127
	s_lshl_b32 s41, s76, 14
	v_add_u32_e32 v233, s41, v187
	ds_read_b64_tr_b16 v[166:167], v233 offset:0
	ds_read_b64_tr_b16 v[168:169], v233 offset:0x800
	ds_read_b64_tr_b16 v[170:171], v233 offset:0x1000
	ds_read_b64_tr_b16 v[172:173], v233 offset:0x1800
	ds_read_b64_tr_b16 v[174:175], v233 offset:0x2000
	ds_read_b64_tr_b16 v[176:177], v233 offset:0x2800
	ds_read_b64_tr_b16 v[178:179], v233 offset:0x3000
	ds_read_b64_tr_b16 v[180:181], v233 offset:0x3800
	s_setprio 1
	s_waitcnt lgkmcnt(6)
	v_mfma_f32_32x32x16_bf16 v[48:63], v[112:115], v[166:169], v[48:63]
	s_waitcnt lgkmcnt(4)
	v_mfma_f32_32x32x16_bf16 v[48:63], v[116:119], v[170:173], v[48:63]
	s_waitcnt lgkmcnt(2)
	v_mfma_f32_32x32x16_bf16 v[48:63], v[120:123], v[174:177], v[48:63]
	s_waitcnt lgkmcnt(0)
	v_mfma_f32_32x32x16_bf16 v[48:63], v[124:127], v[178:181], v[48:63]
	s_setprio 0
	v_max3_f32 v166, v80, v81, v82
	v_max3_f32 v167, v64, v65, v66
	v_max_f32_e32 v168, v79, v79
	v_max3_f32 v166, v166, v83, v84
	v_max3_f32 v167, v167, v67, v68
	v_max_f32_e32 v169, v95, v95
	v_max3_f32 v166, v166, v85, v86
	v_max3_f32 v167, v167, v69, v70
	v_max_f32_e32 v168, v169, v168
	v_max3_f32 v166, v166, v87, v88
	v_max3_f32 v167, v167, v71, v72
	s_nop 0
	v_max3_f32 v166, v166, v89, v90
	v_max3_f32 v167, v167, v73, v74
	s_nop 0
	v_max3_f32 v166, v166, v91, v92
	v_max3_f32 v167, v167, v75, v76
	s_nop 0
	v_max3_f32 v166, v166, v93, v94
	v_max3_f32 v167, v167, v77, v78
	s_nop 0
	v_max3_f32 v166, v166, v167, v168
	s_nop 0
	v_mov_b32_e32 v167, v166
	s_nop 1
	v_permlane32_swap_b32_e32 v166, v167
	v_max_f32_e32 v167, v167, v167
	v_max_f32_e32 v166, v166, v166
	v_max_f32_e32 v227, v166, v167
	ds_read_b64_tr_b16 v[166:167], v233 offset:0x200
	ds_read_b64_tr_b16 v[168:169], v233 offset:0xa00
	ds_read_b64_tr_b16 v[170:171], v233 offset:0x1200
	ds_read_b64_tr_b16 v[172:173], v233 offset:0x1a00
	ds_read_b64_tr_b16 v[174:175], v233 offset:0x2200
	ds_read_b64_tr_b16 v[176:177], v233 offset:0x2a00
	ds_read_b64_tr_b16 v[178:179], v233 offset:0x3200
	ds_read_b64_tr_b16 v[180:181], v233 offset:0x3a00
	s_setprio 1
	s_waitcnt lgkmcnt(6)
	v_mfma_f32_32x32x16_bf16 v[32:47], v[112:115], v[166:169], v[32:47]
	s_waitcnt lgkmcnt(4)
	v_mfma_f32_32x32x16_bf16 v[32:47], v[116:119], v[170:173], v[32:47]
	s_waitcnt lgkmcnt(2)
	v_mfma_f32_32x32x16_bf16 v[32:47], v[120:123], v[174:177], v[32:47]
	s_waitcnt lgkmcnt(0)
	v_mfma_f32_32x32x16_bf16 v[32:47], v[124:127], v[178:181], v[32:47]
	s_setprio 0
	v_sub_f32_e32 v166, v227, v229
	v_cmp_ge_f32_e32 vcc, s71, v166
	s_cmp_eq_u64 vcc, exec
	v_max_f32_e32 v166, v229, v229
	v_max_f32_e32 v232, v166, v227
	s_cselect_b64 s[0:1], -1, 0
	v_cndmask_b32_e64 v227, v232, v229, s[0:1]
	v_mul_f32_e32 v167, 0xbe38aa3b, v227
	v_fma_f32 v80, v80, v197, v167
	v_fma_f32 v81, v81, v197, v167
	v_fma_f32 v82, v82, v197, v167
	v_fma_f32 v83, v83, v197, v167
	v_fma_f32 v84, v84, v197, v167
	v_fma_f32 v85, v85, v197, v167
	v_fma_f32 v86, v86, v197, v167
	v_fma_f32 v87, v87, v197, v167
	v_fma_f32 v88, v88, v197, v167
	v_fma_f32 v89, v89, v197, v167
	v_fma_f32 v90, v90, v197, v167
	v_fma_f32 v91, v91, v197, v167
	v_fma_f32 v92, v92, v197, v167
	v_fma_f32 v93, v93, v197, v167
	v_fma_f32 v94, v94, v197, v167
	v_fma_f32 v95, v95, v197, v167
	v_fma_f32 v180, v64, v197, v167
	v_fma_f32 v181, v65, v197, v167
	v_fma_f32 v178, v66, v197, v167
	v_fma_f32 v179, v67, v197, v167
	v_fma_f32 v176, v68, v197, v167
	v_fma_f32 v177, v69, v197, v167
	v_fma_f32 v174, v70, v197, v167
	v_fma_f32 v175, v71, v197, v167
	v_fma_f32 v172, v72, v197, v167
	v_fma_f32 v173, v73, v197, v167
	v_fma_f32 v170, v74, v197, v167
	v_fma_f32 v171, v75, v197, v167
	v_fma_f32 v168, v76, v197, v167
	v_fma_f32 v169, v77, v197, v167
	v_fma_f32 v166, v78, v197, v167
	v_fma_f32 v167, v79, v197, v167
	ds_read_b64_tr_b16 v[64:65], v233 offset:0x400
	ds_read_b64_tr_b16 v[66:67], v233 offset:0xc00
	ds_read_b64_tr_b16 v[68:69], v233 offset:0x1400
	ds_read_b64_tr_b16 v[70:71], v233 offset:0x1c00
	ds_read_b64_tr_b16 v[72:73], v233 offset:0x2400
	ds_read_b64_tr_b16 v[74:75], v233 offset:0x2c00
	ds_read_b64_tr_b16 v[76:77], v233 offset:0x3400
	ds_read_b64_tr_b16 v[78:79], v233 offset:0x3c00
	s_setprio 1
	s_waitcnt lgkmcnt(6)
	v_mfma_f32_32x32x16_bf16 v[16:31], v[112:115], v[64:67], v[16:31]
	s_waitcnt lgkmcnt(4)
	v_mfma_f32_32x32x16_bf16 v[16:31], v[116:119], v[68:71], v[16:31]
	s_waitcnt lgkmcnt(2)
	v_mfma_f32_32x32x16_bf16 v[16:31], v[120:123], v[72:75], v[16:31]
	s_waitcnt lgkmcnt(0)
	v_mfma_f32_32x32x16_bf16 v[16:31], v[124:127], v[76:79], v[16:31]
	s_setprio 0
	ds_read_b64_tr_b16 v[64:65], v233 offset:0x600
	ds_read_b64_tr_b16 v[66:67], v233 offset:0xe00
	ds_read_b64_tr_b16 v[68:69], v233 offset:0x1600
	ds_read_b64_tr_b16 v[70:71], v233 offset:0x1e00
	ds_read_b64_tr_b16 v[72:73], v233 offset:0x2600
	ds_read_b64_tr_b16 v[74:75], v233 offset:0x2e00
	ds_read_b64_tr_b16 v[76:77], v233 offset:0x3600
	ds_read_b64_tr_b16 v[78:79], v233 offset:0x3e00
	s_setprio 1
	s_waitcnt lgkmcnt(6)
	v_mfma_f32_32x32x16_bf16 v[0:15], v[112:115], v[64:67], v[0:15]
	s_waitcnt lgkmcnt(4)
	v_mfma_f32_32x32x16_bf16 v[0:15], v[116:119], v[68:71], v[0:15]
	s_waitcnt lgkmcnt(2)
	v_mfma_f32_32x32x16_bf16 v[0:15], v[120:123], v[72:75], v[0:15]
	s_waitcnt lgkmcnt(0)
	v_mfma_f32_32x32x16_bf16 v[0:15], v[124:127], v[76:79], v[0:15]
	s_setprio 0
	s_waitcnt vmcnt(0)
	s_barrier
	s_cmp_gt_u32 s37, 28
	s_cselect_b64 s[38:39], -1, 0
	s_and_b64 vcc, exec, s[38:39]
	s_cbranch_vccnz .LBB0_1056
	s_add_i32 s40, s40, s74
	v_lshl_add_u64 v[64:65], v[160:161], 0, s[60:61]
	s_add_i32 m0, s40, 0xc000
	s_add_i32 s40, s75, s41
	global_load_lds_dwordx4 v[64:65], off
	v_lshl_add_u64 v[64:65], v[162:163], 0, s[34:35]
	s_mov_b32 m0, s40
	s_nop 0
	global_load_lds_dwordx4 v[64:65], off
	v_lshl_add_u64 v[64:65], v[164:165], 0, s[34:35]
	s_add_i32 m0, s40, 0x2000
	s_nop 0
	global_load_lds_dwordx4 v[64:65], off
